# prologue: silu staging, pool-map staging loops and the barrier census issue all their loads before waiting (were one dependent round trip per iteration)
# baseline (speedup 1.0000x reference)
; #define LAS __attribute__((address_space(3)))
; __device__ __forceinline__ float silu_f(float v) { return v / (1.f + __expf(-v)); }
; __device__ __forceinline__ void mod_item(const Params& p, LAS unsigned char* lds, int item, int tid, int wave, int lane) {
;     LAS float* sv = (LAS float*)lds;
;     LAS float* part = (LAS float*)(lds + 36864);
;     const int l = item / 24, j0 = (item % 24) * 256;
;     for (int i = tid; i < 9 * 1024; i += NTHR) { const int r = i >> 10, k = i & 1023; const float v = (r < 8) ? p.in[I_C][r * 1024 + k] : p.in[I_CCTX][k]; sv[i] = silu_f(v); }
.LBB0_372:
	global_load_dword v28, v[0:1], off
	global_load_dword v29, v[0:1], off offset:2048
	v_lshl_add_u64 v[4:5], v[0:1], 0, s[90:91]
	v_lshl_add_u64 v[4:5], v[4:5], 0, s[90:91]
	global_load_dword v30, v[4:5], off
	global_load_dword v31, v[4:5], off offset:2048
	v_lshl_add_u64 v[4:5], v[4:5], 0, s[90:91]
	v_lshl_add_u64 v[4:5], v[4:5], 0, s[90:91]
	global_load_dword v32, v[4:5], off
	global_load_dword v33, v[4:5], off offset:2048
	v_lshl_add_u64 v[4:5], v[4:5], 0, s[90:91]
	v_lshl_add_u64 v[4:5], v[4:5], 0, s[90:91]
	global_load_dword v34, v[4:5], off
	global_load_dword v35, v[4:5], off offset:2048
	v_lshl_add_u64 v[4:5], v[4:5], 0, s[90:91]
	v_lshl_add_u64 v[4:5], v[4:5], 0, s[90:91]
	global_load_dword v36, v[4:5], off
	global_load_dword v37, v[4:5], off offset:2048
	v_lshl_add_u64 v[4:5], v[4:5], 0, s[90:91]
	v_lshl_add_u64 v[4:5], v[4:5], 0, s[90:91]
	global_load_dword v38, v[4:5], off
	global_load_dword v39, v[4:5], off offset:2048
	v_lshl_add_u64 v[4:5], v[4:5], 0, s[90:91]
	v_lshl_add_u64 v[4:5], v[4:5], 0, s[90:91]
	global_load_dword v60, v[4:5], off
	global_load_dword v61, v[4:5], off offset:2048
	v_lshl_add_u64 v[4:5], v[4:5], 0, s[90:91]
	v_lshl_add_u64 v[4:5], v[4:5], 0, s[90:91]
	global_load_dword v62, v[4:5], off
	global_load_dword v63, v[4:5], off offset:2048
	v_lshlrev_b32_e32 v156, 2, v166
	v_lshl_add_u64 v[4:5], s[0:1], 0, v[156:157]
	global_load_dword v64, v[4:5], off
	global_load_dword v65, v[4:5], off offset:2048
	s_waitcnt vmcnt(0)
	v_mul_f32_e32 v5, 0xbfb8aa3b, v28
	v_exp_f32_e32 v5, v5
	s_nop 0
	v_add_f32_e32 v5, 1.0, v5
	v_div_scale_f32 v6, s[14:15], v5, v5, v28
	v_rcp_f32_e32 v7, v6
	v_div_scale_f32 v8, vcc, v28, v5, v28
	v_fma_f32 v9, -v6, v7, 1.0
	v_fmac_f32_e32 v7, v9, v7
	v_mul_f32_e32 v9, v8, v7
	v_fma_f32 v10, -v6, v9, v8
	v_fmac_f32_e32 v9, v10, v7
	v_fma_f32 v6, -v6, v9, v8
	v_div_fmas_f32 v6, v6, v7, v9
	v_div_fixup_f32 v4, v6, v5, v28
	ds_write_b32 v2, v4
	v_mul_f32_e32 v5, 0xbfb8aa3b, v29
	v_exp_f32_e32 v5, v5
	s_nop 0
	v_add_f32_e32 v5, 1.0, v5
	v_div_scale_f32 v6, s[14:15], v5, v5, v29
	v_rcp_f32_e32 v7, v6
	v_div_scale_f32 v8, vcc, v29, v5, v29
	v_fma_f32 v9, -v6, v7, 1.0
	v_fmac_f32_e32 v7, v9, v7
	v_mul_f32_e32 v9, v8, v7
	v_fma_f32 v10, -v6, v9, v8
	v_fmac_f32_e32 v9, v10, v7
	v_fma_f32 v6, -v6, v9, v8
	v_div_fmas_f32 v6, v6, v7, v9
	v_div_fixup_f32 v4, v6, v5, v29
	ds_write_b32 v2, v4 offset:2048
	v_mul_f32_e32 v5, 0xbfb8aa3b, v30
	v_exp_f32_e32 v5, v5
	s_nop 0
	v_add_f32_e32 v5, 1.0, v5
	v_div_scale_f32 v6, s[14:15], v5, v5, v30
	v_rcp_f32_e32 v7, v6
	v_div_scale_f32 v8, vcc, v30, v5, v30
	v_fma_f32 v9, -v6, v7, 1.0
	v_fmac_f32_e32 v7, v9, v7
	v_mul_f32_e32 v9, v8, v7
	v_fma_f32 v10, -v6, v9, v8
	v_fmac_f32_e32 v9, v10, v7
	v_fma_f32 v6, -v6, v9, v8
	v_div_fmas_f32 v6, v6, v7, v9
	v_div_fixup_f32 v4, v6, v5, v30
	ds_write_b32 v2, v4 offset:4096
	v_mul_f32_e32 v5, 0xbfb8aa3b, v31
	v_exp_f32_e32 v5, v5
	s_nop 0
	v_add_f32_e32 v5, 1.0, v5
	v_div_scale_f32 v6, s[14:15], v5, v5, v31
	v_rcp_f32_e32 v7, v6
	v_div_scale_f32 v8, vcc, v31, v5, v31
	v_fma_f32 v9, -v6, v7, 1.0
	v_fmac_f32_e32 v7, v9, v7
	v_mul_f32_e32 v9, v8, v7
	v_fma_f32 v10, -v6, v9, v8
	v_fmac_f32_e32 v9, v10, v7
	v_fma_f32 v6, -v6, v9, v8
	v_div_fmas_f32 v6, v6, v7, v9
	v_div_fixup_f32 v4, v6, v5, v31
	ds_write_b32 v2, v4 offset:6144
	v_mul_f32_e32 v5, 0xbfb8aa3b, v32
	v_exp_f32_e32 v5, v5
	s_nop 0
	v_add_f32_e32 v5, 1.0, v5
	v_div_scale_f32 v6, s[14:15], v5, v5, v32
	v_rcp_f32_e32 v7, v6
	v_div_scale_f32 v8, vcc, v32, v5, v32
	v_fma_f32 v9, -v6, v7, 1.0
	v_fmac_f32_e32 v7, v9, v7
	v_mul_f32_e32 v9, v8, v7
	v_fma_f32 v10, -v6, v9, v8
	v_fmac_f32_e32 v9, v10, v7
	v_fma_f32 v6, -v6, v9, v8
	v_div_fmas_f32 v6, v6, v7, v9
	v_div_fixup_f32 v4, v6, v5, v32
	ds_write_b32 v2, v4 offset:8192
	v_mul_f32_e32 v5, 0xbfb8aa3b, v33
	v_exp_f32_e32 v5, v5
	s_nop 0
	v_add_f32_e32 v5, 1.0, v5
	v_div_scale_f32 v6, s[14:15], v5, v5, v33
	v_rcp_f32_e32 v7, v6
	v_div_scale_f32 v8, vcc, v33, v5, v33
	v_fma_f32 v9, -v6, v7, 1.0
	v_fmac_f32_e32 v7, v9, v7
	v_mul_f32_e32 v9, v8, v7
	v_fma_f32 v10, -v6, v9, v8
	v_fmac_f32_e32 v9, v10, v7
	v_fma_f32 v6, -v6, v9, v8
	v_div_fmas_f32 v6, v6, v7, v9
	v_div_fixup_f32 v4, v6, v5, v33
	ds_write_b32 v2, v4 offset:10240
	v_mul_f32_e32 v5, 0xbfb8aa3b, v34
	v_exp_f32_e32 v5, v5
	s_nop 0
	v_add_f32_e32 v5, 1.0, v5
	v_div_scale_f32 v6, s[14:15], v5, v5, v34
	v_rcp_f32_e32 v7, v6
	v_div_scale_f32 v8, vcc, v34, v5, v34
	v_fma_f32 v9, -v6, v7, 1.0
	v_fmac_f32_e32 v7, v9, v7
	v_mul_f32_e32 v9, v8, v7
	v_fma_f32 v10, -v6, v9, v8
	v_fmac_f32_e32 v9, v10, v7
	v_fma_f32 v6, -v6, v9, v8
	v_div_fmas_f32 v6, v6, v7, v9
	v_div_fixup_f32 v4, v6, v5, v34
	ds_write_b32 v2, v4 offset:12288
	v_mul_f32_e32 v5, 0xbfb8aa3b, v35
	v_exp_f32_e32 v5, v5
	s_nop 0
	v_add_f32_e32 v5, 1.0, v5
	v_div_scale_f32 v6, s[14:15], v5, v5, v35
	v_rcp_f32_e32 v7, v6
	v_div_scale_f32 v8, vcc, v35, v5, v35
; #define LAS __attribute__((address_space(3)))
; __device__ __forceinline__ float silu_f(float v) { return v / (1.f + __expf(-v)); }
; __device__ __forceinline__ void mod_item(const Params& p, LAS unsigned char* lds, int item, int tid, int wave, int lane) {
;     LAS float* sv = (LAS float*)lds;
;     LAS float* part = (LAS float*)(lds + 36864);
;     const int l = item / 24, j0 = (item % 24) * 256;
;     for (int i = tid; i < 9 * 1024; i += NTHR) { const int r = i >> 10, k = i & 1023; const float v = (r < 8) ? p.in[I_C][r * 1024 + k] : p.in[I_CCTX][k]; sv[i] = silu_f(v); }
	v_fma_f32 v9, -v6, v7, 1.0
	v_fmac_f32_e32 v7, v9, v7
	v_mul_f32_e32 v9, v8, v7
	v_fma_f32 v10, -v6, v9, v8
	v_fmac_f32_e32 v9, v10, v7
	v_fma_f32 v6, -v6, v9, v8
	v_div_fmas_f32 v6, v6, v7, v9
	v_div_fixup_f32 v4, v6, v5, v35
	ds_write_b32 v2, v4 offset:14336
	v_mul_f32_e32 v5, 0xbfb8aa3b, v36
	v_exp_f32_e32 v5, v5
	s_nop 0
	v_add_f32_e32 v5, 1.0, v5
	v_div_scale_f32 v6, s[14:15], v5, v5, v36
	v_rcp_f32_e32 v7, v6
	v_div_scale_f32 v8, vcc, v36, v5, v36
	v_fma_f32 v9, -v6, v7, 1.0
	v_fmac_f32_e32 v7, v9, v7
	v_mul_f32_e32 v9, v8, v7
	v_fma_f32 v10, -v6, v9, v8
	v_fmac_f32_e32 v9, v10, v7
	v_fma_f32 v6, -v6, v9, v8
	v_div_fmas_f32 v6, v6, v7, v9
	v_div_fixup_f32 v4, v6, v5, v36
	ds_write_b32 v2, v4 offset:16384
	v_mul_f32_e32 v5, 0xbfb8aa3b, v37
	v_exp_f32_e32 v5, v5
	s_nop 0
	v_add_f32_e32 v5, 1.0, v5
	v_div_scale_f32 v6, s[14:15], v5, v5, v37
	v_rcp_f32_e32 v7, v6
	v_div_scale_f32 v8, vcc, v37, v5, v37
	v_fma_f32 v9, -v6, v7, 1.0
	v_fmac_f32_e32 v7, v9, v7
	v_mul_f32_e32 v9, v8, v7
	v_fma_f32 v10, -v6, v9, v8
	v_fmac_f32_e32 v9, v10, v7
	v_fma_f32 v6, -v6, v9, v8
	v_div_fmas_f32 v6, v6, v7, v9
	v_div_fixup_f32 v4, v6, v5, v37
	ds_write_b32 v2, v4 offset:18432
	v_mul_f32_e32 v5, 0xbfb8aa3b, v38
	v_exp_f32_e32 v5, v5
	s_nop 0
	v_add_f32_e32 v5, 1.0, v5
	v_div_scale_f32 v6, s[14:15], v5, v5, v38
	v_rcp_f32_e32 v7, v6
	v_div_scale_f32 v8, vcc, v38, v5, v38
	v_fma_f32 v9, -v6, v7, 1.0
	v_fmac_f32_e32 v7, v9, v7
	v_mul_f32_e32 v9, v8, v7
	v_fma_f32 v10, -v6, v9, v8
	v_fmac_f32_e32 v9, v10, v7
	v_fma_f32 v6, -v6, v9, v8
	v_div_fmas_f32 v6, v6, v7, v9
	v_div_fixup_f32 v4, v6, v5, v38
	ds_write_b32 v2, v4 offset:20480
	v_mul_f32_e32 v5, 0xbfb8aa3b, v39
	v_exp_f32_e32 v5, v5
	s_nop 0
	v_add_f32_e32 v5, 1.0, v5
	v_div_scale_f32 v6, s[14:15], v5, v5, v39
	v_rcp_f32_e32 v7, v6
	v_div_scale_f32 v8, vcc, v39, v5, v39
	v_fma_f32 v9, -v6, v7, 1.0
	v_fmac_f32_e32 v7, v9, v7
	v_mul_f32_e32 v9, v8, v7
	v_fma_f32 v10, -v6, v9, v8
	v_fmac_f32_e32 v9, v10, v7
	v_fma_f32 v6, -v6, v9, v8
	v_div_fmas_f32 v6, v6, v7, v9
	v_div_fixup_f32 v4, v6, v5, v39
	ds_write_b32 v2, v4 offset:22528
	v_mul_f32_e32 v5, 0xbfb8aa3b, v60
	v_exp_f32_e32 v5, v5
	s_nop 0
	v_add_f32_e32 v5, 1.0, v5
	v_div_scale_f32 v6, s[14:15], v5, v5, v60
	v_rcp_f32_e32 v7, v6
	v_div_scale_f32 v8, vcc, v60, v5, v60
	v_fma_f32 v9, -v6, v7, 1.0
	v_fmac_f32_e32 v7, v9, v7
	v_mul_f32_e32 v9, v8, v7
	v_fma_f32 v10, -v6, v9, v8
	v_fmac_f32_e32 v9, v10, v7
	v_fma_f32 v6, -v6, v9, v8
	v_div_fmas_f32 v6, v6, v7, v9
	v_div_fixup_f32 v4, v6, v5, v60
	ds_write_b32 v2, v4 offset:24576
	v_mul_f32_e32 v5, 0xbfb8aa3b, v61
	v_exp_f32_e32 v5, v5
	s_nop 0
	v_add_f32_e32 v5, 1.0, v5
	v_div_scale_f32 v6, s[14:15], v5, v5, v61
	v_rcp_f32_e32 v7, v6
	v_div_scale_f32 v8, vcc, v61, v5, v61
	v_fma_f32 v9, -v6, v7, 1.0
	v_fmac_f32_e32 v7, v9, v7
	v_mul_f32_e32 v9, v8, v7
	v_fma_f32 v10, -v6, v9, v8
	v_fmac_f32_e32 v9, v10, v7
	v_fma_f32 v6, -v6, v9, v8
	v_div_fmas_f32 v6, v6, v7, v9
	v_div_fixup_f32 v4, v6, v5, v61
	ds_write_b32 v2, v4 offset:26624
	v_mul_f32_e32 v5, 0xbfb8aa3b, v62
	v_exp_f32_e32 v5, v5
	s_nop 0
	v_add_f32_e32 v5, 1.0, v5
	v_div_scale_f32 v6, s[14:15], v5, v5, v62
	v_rcp_f32_e32 v7, v6
	v_div_scale_f32 v8, vcc, v62, v5, v62
	v_fma_f32 v9, -v6, v7, 1.0
	v_fmac_f32_e32 v7, v9, v7
	v_mul_f32_e32 v9, v8, v7
	v_fma_f32 v10, -v6, v9, v8
	v_fmac_f32_e32 v9, v10, v7
	v_fma_f32 v6, -v6, v9, v8
	v_div_fmas_f32 v6, v6, v7, v9
	v_div_fixup_f32 v4, v6, v5, v62
	ds_write_b32 v2, v4 offset:28672
	v_mul_f32_e32 v5, 0xbfb8aa3b, v63
	v_exp_f32_e32 v5, v5
	s_nop 0
	v_add_f32_e32 v5, 1.0, v5
	v_div_scale_f32 v6, s[14:15], v5, v5, v63
	v_rcp_f32_e32 v7, v6
	v_div_scale_f32 v8, vcc, v63, v5, v63
	v_fma_f32 v9, -v6, v7, 1.0
	v_fmac_f32_e32 v7, v9, v7
	v_mul_f32_e32 v9, v8, v7
	v_fma_f32 v10, -v6, v9, v8
	v_fmac_f32_e32 v9, v10, v7
	v_fma_f32 v6, -v6, v9, v8
	v_div_fmas_f32 v6, v6, v7, v9
	v_div_fixup_f32 v4, v6, v5, v63
	ds_write_b32 v2, v4 offset:30720
	v_mul_f32_e32 v5, 0xbfb8aa3b, v64
	v_exp_f32_e32 v5, v5
	s_nop 0
	v_add_f32_e32 v5, 1.0, v5
	v_div_scale_f32 v6, s[14:15], v5, v5, v64
	v_rcp_f32_e32 v7, v6
	v_div_scale_f32 v8, vcc, v64, v5, v64
	v_fma_f32 v9, -v6, v7, 1.0
	v_fmac_f32_e32 v7, v9, v7
	v_mul_f32_e32 v9, v8, v7
	v_fma_f32 v10, -v6, v9, v8
	v_fmac_f32_e32 v9, v10, v7
	v_fma_f32 v6, -v6, v9, v8
	v_div_fmas_f32 v6, v6, v7, v9
	v_div_fixup_f32 v4, v6, v5, v64
	ds_write_b32 v2, v4 offset:32768
	v_mul_f32_e32 v5, 0xbfb8aa3b, v65
	v_exp_f32_e32 v5, v5
	s_nop 0
	v_add_f32_e32 v5, 1.0, v5
	v_div_scale_f32 v6, s[14:15], v5, v5, v65
	v_rcp_f32_e32 v7, v6
	v_div_scale_f32 v8, vcc, v65, v5, v65
	v_fma_f32 v9, -v6, v7, 1.0
	v_fmac_f32_e32 v7, v9, v7
	v_mul_f32_e32 v9, v8, v7
	v_fma_f32 v10, -v6, v9, v8
	v_fmac_f32_e32 v9, v10, v7
	v_fma_f32 v6, -v6, v9, v8
	v_div_fmas_f32 v6, v6, v7, v9
	v_div_fixup_f32 v4, v6, v5, v65
	ds_write_b32 v2, v4 offset:34816

; __device__ __forceinline__ void weff_item(const Params& p, LAS unsigned char* lds, int item, int tid, int wave, int lane) {
;     ...
;     const int l = item >> 6, g = (item >> 4) & 3, n0 = (item & 15) * 64;
;     const float* pwg = p.in[I_POOLW] + ((size_t)l * 4 + g) * 128 * 128;
;     for (int i = tid; i < 128 * 128; i += NTHR) pw[(i >> 7) * 129 + (i & 127)] = pwg[i];
.LBB0_383:
	v_lshlrev_b32_e32 v2, 2, v166
	v_ashrrev_i32_e32 v3, 7, v166
	v_mad_u32_u24 v3, v3, s66, v0
	global_load_dword v10, v2, s[24:25]
	global_load_dword v11, v2, s[24:25] offset:2048
	v_add_u32_e32 v2, 0x1000, v2
	global_load_dword v12, v2, s[24:25]
	global_load_dword v13, v2, s[24:25] offset:2048
	v_add_u32_e32 v2, 0x1000, v2
	global_load_dword v14, v2, s[24:25]
	global_load_dword v15, v2, s[24:25] offset:2048
	v_add_u32_e32 v2, 0x1000, v2
	global_load_dword v16, v2, s[24:25]
	global_load_dword v17, v2, s[24:25] offset:2048
	v_add_u32_e32 v2, 0x1000, v2
	global_load_dword v18, v2, s[24:25]
	global_load_dword v19, v2, s[24:25] offset:2048
	v_add_u32_e32 v2, 0x1000, v2
	global_load_dword v20, v2, s[24:25]
	global_load_dword v21, v2, s[24:25] offset:2048
	v_add_u32_e32 v2, 0x1000, v2
	global_load_dword v22, v2, s[24:25]
	global_load_dword v23, v2, s[24:25] offset:2048
	v_add_u32_e32 v2, 0x1000, v2
	global_load_dword v24, v2, s[24:25]
	global_load_dword v26, v2, s[24:25] offset:2048
	v_add_u32_e32 v2, 0x1000, v2
	global_load_dword v27, v2, s[24:25]
	global_load_dword v28, v2, s[24:25] offset:2048
	v_add_u32_e32 v2, 0x1000, v2
	global_load_dword v29, v2, s[24:25]
	global_load_dword v30, v2, s[24:25] offset:2048
	v_add_u32_e32 v2, 0x1000, v2
	global_load_dword v31, v2, s[24:25]
	global_load_dword v32, v2, s[24:25] offset:2048
	v_add_u32_e32 v2, 0x1000, v2
	global_load_dword v33, v2, s[24:25]
	global_load_dword v34, v2, s[24:25] offset:2048
	v_add_u32_e32 v2, 0x1000, v2
	global_load_dword v35, v2, s[24:25]
	global_load_dword v36, v2, s[24:25] offset:2048
	v_add_u32_e32 v2, 0x1000, v2
	global_load_dword v37, v2, s[24:25]
	global_load_dword v38, v2, s[24:25] offset:2048
	v_add_u32_e32 v2, 0x1000, v2
	global_load_dword v39, v2, s[24:25]
	global_load_dword v40, v2, s[24:25] offset:2048
	v_add_u32_e32 v2, 0x1000, v2
	global_load_dword v41, v2, s[24:25]
	global_load_dword v42, v2, s[24:25] offset:2048
	s_waitcnt vmcnt(0)
	ds_write_b32 v3, v10
	ds_write_b32 v3, v11 offset:2064
	ds_write_b32 v3, v12 offset:4128
	ds_write_b32 v3, v13 offset:6192
	ds_write_b32 v3, v14 offset:8256
	ds_write_b32 v3, v15 offset:10320
	ds_write_b32 v3, v16 offset:12384
	ds_write_b32 v3, v17 offset:14448
	ds_write_b32 v3, v18 offset:16512
	ds_write_b32 v3, v19 offset:18576
	ds_write_b32 v3, v20 offset:20640
	ds_write_b32 v3, v21 offset:22704
	ds_write_b32 v3, v22 offset:24768
	ds_write_b32 v3, v23 offset:26832
	ds_write_b32 v3, v24 offset:28896
	ds_write_b32 v3, v26 offset:30960
	ds_write_b32 v3, v27 offset:33024
	ds_write_b32 v3, v28 offset:35088
	ds_write_b32 v3, v29 offset:37152
	ds_write_b32 v3, v30 offset:39216
	ds_write_b32 v3, v31 offset:41280
	ds_write_b32 v3, v32 offset:43344
	ds_write_b32 v3, v33 offset:45408
	ds_write_b32 v3, v34 offset:47472
	ds_write_b32 v3, v35 offset:49536
	ds_write_b32 v3, v36 offset:51600
	ds_write_b32 v3, v37 offset:53664
	ds_write_b32 v3, v38 offset:55728
	ds_write_b32 v3, v39 offset:57792
	ds_write_b32 v3, v40 offset:59856
	ds_write_b32 v3, v41 offset:61920
	ds_write_b32 v3, v42 offset:63984
	s_or_b64 exec, exec, s[26:27]
	s_orn2_b64 s[0:1], s[8:9], exec
	v_mov_b32_e32 v2, v25

; __device__ __forceinline__ void weff_item(const Params& p, LAS unsigned char* lds, int item, int tid, int wave, int lane) {
;     ...
;     const float* wog = p.in[I_WOUT] + (size_t)l * DM * DM + (size_t)(g * 128) * DM + n0;
;     const float* psg = p.in[I_POOLS] + l * 512 + g * 128;
;     for (int i = tid; i < 128 * 64; i += NTHR) { const int d = i >> 6, n = i & 63; wo[i] = wog[(size_t)d * DM + n] * psg[d]; }
;     __syncthreads();
.LBB0_391:
	v_ashrrev_i32_e32 v6, 6, v166
	v_lshlrev_b32_e32 v7, 2, v6
	v_lshlrev_b32_e32 v8, 12, v6
	v_mov_b32_e32 v9, v157
	v_lshl_add_u64 v[4:5], v[2:3], 0, v[8:9]
	v_add_u32_e32 v6, 0xfffff800, v51
	global_load_dword v10, v7, s[20:21]
	global_load_dword v11, v7, s[20:21] offset:32
	global_load_dword v12, v7, s[20:21] offset:64
	global_load_dword v13, v7, s[20:21] offset:96
	global_load_dword v14, v7, s[20:21] offset:128
	global_load_dword v15, v7, s[20:21] offset:160
	global_load_dword v16, v7, s[20:21] offset:192
	global_load_dword v17, v7, s[20:21] offset:224
	global_load_dword v18, v7, s[20:21] offset:256
	global_load_dword v19, v7, s[20:21] offset:288
	global_load_dword v20, v7, s[20:21] offset:320
	global_load_dword v21, v7, s[20:21] offset:352
	global_load_dword v22, v7, s[20:21] offset:384
	global_load_dword v23, v7, s[20:21] offset:416
	global_load_dword v24, v7, s[20:21] offset:448
	global_load_dword v43, v7, s[20:21] offset:480
	global_load_dword v26, v[4:5], off
	v_add_co_u32_e32 v4, vcc, 0x8000, v4
	s_nop 1
	v_addc_co_u32_e32 v5, vcc, 0, v5, vcc
	global_load_dword v27, v[4:5], off
	v_add_co_u32_e32 v4, vcc, 0x8000, v4
	s_nop 1
	v_addc_co_u32_e32 v5, vcc, 0, v5, vcc
	global_load_dword v28, v[4:5], off
	v_add_co_u32_e32 v4, vcc, 0x8000, v4
	s_nop 1
	v_addc_co_u32_e32 v5, vcc, 0, v5, vcc
	global_load_dword v29, v[4:5], off
	v_add_co_u32_e32 v4, vcc, 0x8000, v4
	s_nop 1
	v_addc_co_u32_e32 v5, vcc, 0, v5, vcc
	global_load_dword v30, v[4:5], off
	v_add_co_u32_e32 v4, vcc, 0x8000, v4
	s_nop 1
	v_addc_co_u32_e32 v5, vcc, 0, v5, vcc
	global_load_dword v31, v[4:5], off
	v_add_co_u32_e32 v4, vcc, 0x8000, v4
	s_nop 1
	v_addc_co_u32_e32 v5, vcc, 0, v5, vcc
	global_load_dword v32, v[4:5], off
	v_add_co_u32_e32 v4, vcc, 0x8000, v4
	s_nop 1
	v_addc_co_u32_e32 v5, vcc, 0, v5, vcc
	global_load_dword v33, v[4:5], off
	v_add_co_u32_e32 v4, vcc, 0x8000, v4
	s_nop 1
	v_addc_co_u32_e32 v5, vcc, 0, v5, vcc
	global_load_dword v34, v[4:5], off
	v_add_co_u32_e32 v4, vcc, 0x8000, v4
	s_nop 1
	v_addc_co_u32_e32 v5, vcc, 0, v5, vcc
	global_load_dword v35, v[4:5], off
	v_add_co_u32_e32 v4, vcc, 0x8000, v4
	s_nop 1
	v_addc_co_u32_e32 v5, vcc, 0, v5, vcc
	global_load_dword v36, v[4:5], off
	v_add_co_u32_e32 v4, vcc, 0x8000, v4
	s_nop 1
	v_addc_co_u32_e32 v5, vcc, 0, v5, vcc
	global_load_dword v37, v[4:5], off
	v_add_co_u32_e32 v4, vcc, 0x8000, v4
	s_nop 1
	v_addc_co_u32_e32 v5, vcc, 0, v5, vcc
	global_load_dword v38, v[4:5], off
	v_add_co_u32_e32 v4, vcc, 0x8000, v4
	s_nop 1
	v_addc_co_u32_e32 v5, vcc, 0, v5, vcc
	global_load_dword v39, v[4:5], off
	v_add_co_u32_e32 v4, vcc, 0x8000, v4
	s_nop 1
	v_addc_co_u32_e32 v5, vcc, 0, v5, vcc
	global_load_dword v40, v[4:5], off
	v_add_co_u32_e32 v4, vcc, 0x8000, v4
	s_nop 1
	v_addc_co_u32_e32 v5, vcc, 0, v5, vcc
	global_load_dword v41, v[4:5], off
	s_waitcnt vmcnt(0)
	v_mul_f32_e32 v26, v26, v10
	v_mul_f32_e32 v27, v27, v11
	v_mul_f32_e32 v28, v28, v12
	v_mul_f32_e32 v29, v29, v13
	v_mul_f32_e32 v30, v30, v14
	v_mul_f32_e32 v31, v31, v15
	v_mul_f32_e32 v32, v32, v16
	v_mul_f32_e32 v33, v33, v17
	v_mul_f32_e32 v34, v34, v18
	v_mul_f32_e32 v35, v35, v19
	v_mul_f32_e32 v36, v36, v20
	v_mul_f32_e32 v37, v37, v21
	v_mul_f32_e32 v38, v38, v22
	v_mul_f32_e32 v39, v39, v23
	v_mul_f32_e32 v40, v40, v24
	v_mul_f32_e32 v41, v41, v43
	ds_write_b32 v6, v26
	ds_write_b32 v6, v27 offset:2048
	ds_write_b32 v6, v28 offset:4096
	ds_write_b32 v6, v29 offset:6144
	ds_write_b32 v6, v30 offset:8192
	ds_write_b32 v6, v31 offset:10240
	ds_write_b32 v6, v32 offset:12288
	ds_write_b32 v6, v33 offset:14336
	ds_write_b32 v6, v34 offset:16384
	ds_write_b32 v6, v35 offset:18432
	ds_write_b32 v6, v36 offset:20480
	ds_write_b32 v6, v37 offset:22528
	ds_write_b32 v6, v38 offset:24576
	ds_write_b32 v6, v39 offset:26624
	ds_write_b32 v6, v40 offset:28672
	ds_write_b32 v6, v41 offset:30720
	s_or_b64 exec, exec, s[24:25]
	s_mov_b64 s[0:1], 0
	s_and_saveexec_b64 s[24:25], s[12:13]
	s_mov_b64 s[0:1], exec
	v_lshlrev_b32_e32 v5, 2, v49
	s_or_b64 exec, exec, s[24:25]
	s_orn2_b64 s[0:1], s[0:1], exec
	v_mov_b32_e32 v4, v49

; __device__ __forceinline__ unsigned xb_ld(unsigned* p)              { return __hip_atomic_load(p, __ATOMIC_RELAXED, __HIP_MEMORY_SCOPE_AGENT); }
; __device__ __forceinline__ void xcd_barrier_complete(unsigned* bar, unsigned x, unsigned& nloc, unsigned& nx) {
;     ...
;     for (;;) {
;         sum = 0u; cnt = 0u; mine = 0u;
; #pragma unroll
;         for (unsigned j = 0; j < 16; ++j) { const unsigned c = xb_ld(&bar[XB_XCNT(j)]); sum += c; cnt += (c > 0u) ? 1u : 0u; mine = (j == x) ? c : mine; }
;         if (sum == G) break;
;         __builtin_amdgcn_s_sleep(1);
;         if ((++sp & 255u) == 0u) { if (xb_ld(&bar[XB_TMO])) break; if (sp > XB_SPIN_CAP) { atomicAdd(&bar[XB_TMO], 1u); break; } }
;     }
.LBB0_446:
	v_readlane_b32 s6, v253, 20
	v_readlane_b32 s7, v253, 21
	s_mov_b64 s[8:9], -1
	s_nop 3
	global_load_dword v0, v157, s[6:7] sc1
	v_readlane_b32 s6, v253, 22
	v_readlane_b32 s7, v253, 23
	s_nop 4
	global_load_dword v1, v157, s[6:7] sc1
	v_readlane_b32 s6, v253, 24
	v_readlane_b32 s7, v253, 25
	s_nop 4
	global_load_dword v2, v157, s[6:7] sc1
	v_readlane_b32 s6, v253, 26
	v_readlane_b32 s7, v253, 27
	s_nop 4
	global_load_dword v3, v157, s[6:7] sc1
	v_readlane_b32 s6, v253, 28
	v_readlane_b32 s7, v253, 29
	s_nop 4
	global_load_dword v4, v157, s[6:7] sc1
	v_readlane_b32 s6, v253, 30
	v_readlane_b32 s7, v253, 31
	s_nop 4
	global_load_dword v5, v157, s[6:7] sc1
	v_readlane_b32 s6, v253, 32
	v_readlane_b32 s7, v253, 33
	s_nop 4
	global_load_dword v6, v157, s[6:7] sc1
	v_readlane_b32 s6, v253, 34
	v_readlane_b32 s7, v253, 35
	s_nop 4
	global_load_dword v7, v157, s[6:7] sc1
	v_readlane_b32 s6, v253, 36
	v_readlane_b32 s7, v253, 37
	s_nop 4
	global_load_dword v8, v157, s[6:7] sc1
	v_readlane_b32 s6, v253, 38
	v_readlane_b32 s7, v253, 39
	s_nop 4
	global_load_dword v9, v157, s[6:7] sc1
	v_readlane_b32 s6, v253, 40
	v_readlane_b32 s7, v253, 41
	s_nop 4
	global_load_dword v10, v157, s[6:7] sc1
	v_readlane_b32 s6, v253, 42
	v_readlane_b32 s7, v253, 43
	s_nop 4
	global_load_dword v11, v157, s[6:7] sc1
	v_readlane_b32 s6, v253, 44
	v_readlane_b32 s7, v253, 45
	s_nop 4
	global_load_dword v12, v157, s[6:7] sc1
	v_readlane_b32 s6, v253, 46
	v_readlane_b32 s7, v253, 47
	s_nop 4
	global_load_dword v13, v157, s[6:7] sc1
	v_readlane_b32 s6, v253, 48
	v_readlane_b32 s7, v253, 49
	s_nop 4
	global_load_dword v14, v157, s[6:7] sc1
	v_readlane_b32 s6, v253, 50
	v_readlane_b32 s7, v253, 51
	s_nop 4
	global_load_dword v15, v157, s[6:7] sc1
	s_mov_b64 s[6:7], -1
	s_waitcnt vmcnt(0)
	v_add_u32_e32 v16, v1, v0
	v_add_u32_e32 v16, v16, v2
	v_add_u32_e32 v16, v16, v3
	v_add_u32_e32 v16, v16, v4
	v_add_u32_e32 v16, v16, v5
	v_add_u32_e32 v16, v16, v6
	v_add_u32_e32 v16, v16, v7
	v_add_u32_e32 v16, v16, v8
	v_add_u32_e32 v16, v16, v9
	v_add_u32_e32 v16, v16, v10
	v_add_u32_e32 v16, v16, v11
	v_add_u32_e32 v16, v16, v12
	v_add_u32_e32 v16, v16, v13
	v_add_u32_e32 v16, v16, v14
	v_add_u32_e32 v16, v16, v15
	v_cmp_eq_u32_e32 vcc, s12, v16
	s_cbranch_vccnz .LBB0_445
	s_and_b32 s6, s13, 0xff
	s_cmp_eq_u32 s6, 0
	s_mov_b64 s[6:7], -1
	s_mov_b64 s[10:11], -1
	s_sleep 1
	s_cbranch_scc0 .LBB0_450
	v_readlane_b32 s6, v253, 18
	v_readlane_b32 s7, v253, 19
	s_nop 4
	global_load_dword v16, v157, s[6:7] sc1
	s_waitcnt vmcnt(0)
	v_cmp_eq_u32_e32 vcc, 0, v16
	s_cbranch_vccnz .LBB0_452
	s_mov_b64 s[10:11], 0
	s_mov_b64 s[6:7], -1
